# GEMM K-loop heads aligned to 64 bytes (.p2align 6 before the four loop labels)
# speedup vs baseline: 1.0054x; 1.0054x over previous
.LBB0_172:
	v_mov_b64_e32 v[0:1], 0x1080
	s_ashr_i32 s57, s56, 31
	v_cmp_lt_i64_e32 vcc, s[58:59], v[0:1]
	s_lshl_b64 s[58:59], s[56:57], 20
	v_readlane_b32 s34, v255, 26
	v_readlane_b32 s35, v255, 27
	s_add_u32 s58, s34, s58
	s_addc_u32 s59, s35, s59
	s_and_b64 s[60:61], vcc, exec
	s_cselect_b32 s57, s59, s63
	s_cselect_b32 s71, s58, s62
	s_ashr_i32 s55, s54, 31
	s_lshl_b64 s[60:61], s[54:55], 20
	s_add_u32 s60, s33, s60
	s_addc_u32 s61, s37, s61
	s_and_b64 s[66:67], vcc, exec
	s_cselect_b32 s55, s61, s65
	s_cselect_b32 s80, s60, s64
	s_add_u32 s81, s64, 0x100
	v_mov_b32_e32 v0, 0
	s_addc_u32 s82, s65, 0
	s_mov_b32 s83, -2
	v_mov_b32_e32 v1, v0
	v_mov_b32_e32 v2, v0
	v_mov_b32_e32 v3, v0
	v_mov_b32_e32 v64, v0
	v_mov_b32_e32 v65, v0
	v_mov_b32_e32 v66, v0
	v_mov_b32_e32 v67, v0
	v_mov_b32_e32 v4, v0
	v_mov_b32_e32 v5, v0
	v_mov_b32_e32 v6, v0
	v_mov_b32_e32 v7, v0
	v_mov_b32_e32 v68, v0
	v_mov_b32_e32 v69, v0
	v_mov_b32_e32 v70, v0
	v_mov_b32_e32 v71, v0
	v_mov_b32_e32 v32, v0
	v_mov_b32_e32 v33, v0
	v_mov_b32_e32 v34, v0
	v_mov_b32_e32 v35, v0
	v_mov_b32_e32 v110, v0
	v_mov_b32_e32 v111, v0
	v_mov_b32_e32 v112, v0
	v_mov_b32_e32 v113, v0
	v_mov_b32_e32 v36, v0
	v_mov_b32_e32 v37, v0
	v_mov_b32_e32 v38, v0
	v_mov_b32_e32 v39, v0
	v_mov_b32_e32 v114, v0
	v_mov_b32_e32 v115, v0
	v_mov_b32_e32 v116, v0
	v_mov_b32_e32 v117, v0
	v_mov_b32_e32 v8, v0
	v_mov_b32_e32 v9, v0
	v_mov_b32_e32 v10, v0
	v_mov_b32_e32 v11, v0
	v_mov_b32_e32 v72, v0
	v_mov_b32_e32 v73, v0
	v_mov_b32_e32 v74, v0
	v_mov_b32_e32 v75, v0
	v_mov_b32_e32 v12, v0
	v_mov_b32_e32 v13, v0
	v_mov_b32_e32 v14, v0
	v_mov_b32_e32 v15, v0
	v_mov_b32_e32 v76, v0
	v_mov_b32_e32 v77, v0
	v_mov_b32_e32 v78, v0
	v_mov_b32_e32 v79, v0
	v_mov_b32_e32 v16, v0
	v_mov_b32_e32 v17, v0
	v_mov_b32_e32 v18, v0
	v_mov_b32_e32 v19, v0
	v_mov_b32_e32 v80, v0
	v_mov_b32_e32 v81, v0
	v_mov_b32_e32 v82, v0
	v_mov_b32_e32 v83, v0
	v_mov_b32_e32 v20, v0
	v_mov_b32_e32 v21, v0
	v_mov_b32_e32 v22, v0
	v_mov_b32_e32 v23, v0
	v_mov_b32_e32 v84, v0
	v_mov_b32_e32 v85, v0
	v_mov_b32_e32 v86, v0
	v_mov_b32_e32 v87, v0
	v_mov_b32_e32 v24, v0
	v_mov_b32_e32 v25, v0
	v_mov_b32_e32 v26, v0
	v_mov_b32_e32 v27, v0
	v_mov_b32_e32 v88, v0
	v_mov_b32_e32 v89, v0
	v_mov_b32_e32 v90, v0
	v_mov_b32_e32 v91, v0
	v_mov_b32_e32 v28, v0
	v_mov_b32_e32 v29, v0
	v_mov_b32_e32 v30, v0
	v_mov_b32_e32 v31, v0
	v_mov_b32_e32 v92, v0
	v_mov_b32_e32 v93, v0
	v_mov_b32_e32 v94, v0
	v_mov_b32_e32 v95, v0
	v_mov_b32_e32 v40, v0
	v_mov_b32_e32 v41, v0
	v_mov_b32_e32 v42, v0
	v_mov_b32_e32 v43, v0
	v_mov_b32_e32 v118, v0
	v_mov_b32_e32 v119, v0
	v_mov_b32_e32 v120, v0
	v_mov_b32_e32 v121, v0
	v_mov_b32_e32 v44, v0
	v_mov_b32_e32 v45, v0
	v_mov_b32_e32 v46, v0
	v_mov_b32_e32 v47, v0
	v_mov_b32_e32 v122, v0
	v_mov_b32_e32 v123, v0
	v_mov_b32_e32 v124, v0
	v_mov_b32_e32 v125, v0
	v_mov_b32_e32 v48, v0
	v_mov_b32_e32 v49, v0
	v_mov_b32_e32 v50, v0
	v_mov_b32_e32 v51, v0
	v_mov_b32_e32 v126, v0
	v_mov_b32_e32 v127, v0
	v_mov_b32_e32 v128, v0
	v_mov_b32_e32 v129, v0
	v_mov_b32_e32 v52, v0
	v_mov_b32_e32 v53, v0
	v_mov_b32_e32 v54, v0
	v_mov_b32_e32 v55, v0
	v_mov_b32_e32 v130, v0
	v_mov_b32_e32 v131, v0
	v_mov_b32_e32 v132, v0
	v_mov_b32_e32 v133, v0
	v_mov_b32_e32 v56, v0
	v_mov_b32_e32 v57, v0
	v_mov_b32_e32 v58, v0
	v_mov_b32_e32 v59, v0
	v_mov_b32_e32 v134, v0
	v_mov_b32_e32 v135, v0
	v_mov_b32_e32 v136, v0
	v_mov_b32_e32 v137, v0
	v_mov_b32_e32 v60, v0
	v_mov_b32_e32 v61, v0
	v_mov_b32_e32 v62, v0
	v_mov_b32_e32 v63, v0
	v_mov_b32_e32 v138, v0
	v_mov_b32_e32 v139, v0
	v_mov_b32_e32 v140, v0
	v_mov_b32_e32 v141, v0
	.p2align	6

.LBB0_263:
	s_add_u32 s59, s24, 0x100
	s_addc_u32 s60, s25, 0
	s_add_u32 s8, s26, 0x80
	v_mov_b32_e32 v0, 0
	s_addc_u32 s9, s27, 0
	s_mov_b32 s24, 0
	v_mov_b32_e32 v1, v0
	v_mov_b32_e32 v2, v0
	v_mov_b32_e32 v3, v0
	v_mov_b32_e32 v4, v0
	v_mov_b32_e32 v5, v0
	v_mov_b32_e32 v6, v0
	v_mov_b32_e32 v7, v0
	v_mov_b32_e32 v16, v0
	v_mov_b32_e32 v17, v0
	v_mov_b32_e32 v18, v0
	v_mov_b32_e32 v19, v0
	v_mov_b32_e32 v20, v0
	v_mov_b32_e32 v21, v0
	v_mov_b32_e32 v22, v0
	v_mov_b32_e32 v23, v0
	v_mov_b32_e32 v32, v0
	v_mov_b32_e32 v33, v0
	v_mov_b32_e32 v34, v0
	v_mov_b32_e32 v35, v0
	v_mov_b32_e32 v36, v0
	v_mov_b32_e32 v37, v0
	v_mov_b32_e32 v38, v0
	v_mov_b32_e32 v39, v0
	v_mov_b32_e32 v48, v0
	v_mov_b32_e32 v49, v0
	v_mov_b32_e32 v50, v0
	v_mov_b32_e32 v51, v0
	v_mov_b32_e32 v52, v0
	v_mov_b32_e32 v53, v0
	v_mov_b32_e32 v54, v0
	v_mov_b32_e32 v55, v0
	v_mov_b32_e32 v8, v0
	v_mov_b32_e32 v9, v0
	v_mov_b32_e32 v10, v0
	v_mov_b32_e32 v11, v0
	v_mov_b32_e32 v12, v0
	v_mov_b32_e32 v13, v0
	v_mov_b32_e32 v14, v0
	v_mov_b32_e32 v15, v0
	v_mov_b32_e32 v24, v0
	v_mov_b32_e32 v25, v0
	v_mov_b32_e32 v26, v0
	v_mov_b32_e32 v27, v0
	v_mov_b32_e32 v28, v0
	v_mov_b32_e32 v29, v0
	v_mov_b32_e32 v30, v0
	v_mov_b32_e32 v31, v0
	v_mov_b32_e32 v40, v0
	v_mov_b32_e32 v41, v0
	v_mov_b32_e32 v42, v0
	v_mov_b32_e32 v43, v0
	v_mov_b32_e32 v44, v0
	v_mov_b32_e32 v45, v0
	v_mov_b32_e32 v46, v0
	v_mov_b32_e32 v47, v0
	v_mov_b32_e32 v56, v0
	v_mov_b32_e32 v57, v0
	v_mov_b32_e32 v58, v0
	v_mov_b32_e32 v59, v0
	v_mov_b32_e32 v60, v0
	v_mov_b32_e32 v61, v0
	v_mov_b32_e32 v62, v0
	v_mov_b32_e32 v63, v0
	v_mov_b32_e32 v64, v0
	v_mov_b32_e32 v65, v0
	v_mov_b32_e32 v66, v0
	v_mov_b32_e32 v67, v0
	v_mov_b32_e32 v68, v0
	v_mov_b32_e32 v69, v0
	v_mov_b32_e32 v70, v0
	v_mov_b32_e32 v71, v0
	v_mov_b32_e32 v80, v0
	v_mov_b32_e32 v81, v0
	v_mov_b32_e32 v82, v0
	v_mov_b32_e32 v83, v0
	v_mov_b32_e32 v84, v0
	v_mov_b32_e32 v85, v0
	v_mov_b32_e32 v86, v0
	v_mov_b32_e32 v87, v0
	v_mov_b32_e32 v96, v0
	v_mov_b32_e32 v97, v0
	v_mov_b32_e32 v98, v0
	v_mov_b32_e32 v99, v0
	v_mov_b32_e32 v100, v0
	v_mov_b32_e32 v101, v0
	v_mov_b32_e32 v102, v0
	v_mov_b32_e32 v103, v0
	v_mov_b32_e32 v112, v0
	v_mov_b32_e32 v113, v0
	v_mov_b32_e32 v114, v0
	v_mov_b32_e32 v115, v0
	v_mov_b32_e32 v116, v0
	v_mov_b32_e32 v117, v0
	v_mov_b32_e32 v118, v0
	v_mov_b32_e32 v119, v0
	v_mov_b32_e32 v72, v0
	v_mov_b32_e32 v73, v0
	v_mov_b32_e32 v74, v0
	v_mov_b32_e32 v75, v0
	v_mov_b32_e32 v76, v0
	v_mov_b32_e32 v77, v0
	v_mov_b32_e32 v78, v0
	v_mov_b32_e32 v79, v0
	v_mov_b32_e32 v88, v0
	v_mov_b32_e32 v89, v0
	v_mov_b32_e32 v90, v0
	v_mov_b32_e32 v91, v0
	v_mov_b32_e32 v92, v0
	v_mov_b32_e32 v93, v0
	v_mov_b32_e32 v94, v0
	v_mov_b32_e32 v95, v0
	v_mov_b32_e32 v104, v0
	v_mov_b32_e32 v105, v0
	v_mov_b32_e32 v106, v0
	v_mov_b32_e32 v107, v0
	v_mov_b32_e32 v108, v0
	v_mov_b32_e32 v109, v0
	v_mov_b32_e32 v110, v0
	v_mov_b32_e32 v111, v0
	v_mov_b32_e32 v120, v0
	v_mov_b32_e32 v121, v0
	v_mov_b32_e32 v122, v0
	v_mov_b32_e32 v123, v0
	v_mov_b32_e32 v124, v0
	v_mov_b32_e32 v125, v0
	v_mov_b32_e32 v126, v0
	v_mov_b32_e32 v127, v0
	.p2align	6

.LBB0_638:
	v_mov_b64_e32 v[0:1], s[4:5]
	s_ashr_i32 s15, s14, 31
	v_cmp_lt_i64_e32 vcc, s[20:21], v[0:1]
	s_lshl_b64 s[20:21], s[14:15], s50
	s_add_u32 s13, s37, s20
	s_addc_u32 s15, s38, s21
	s_and_b64 s[20:21], vcc, exec
	s_cselect_b32 s21, s15, s27
	s_cselect_b32 s20, s13, s26
	s_ashr_i32 s13, s12, 31
	s_lshl_b64 s[24:25], s[12:13], s50
	s_add_u32 s13, s39, s24
	s_addc_u32 s15, s46, s25
	s_and_b64 s[24:25], vcc, exec
	s_cselect_b32 s25, s15, s31
	s_cselect_b32 s24, s13, s30
	s_add_u32 s26, s26, 0x80
	s_addc_u32 s27, s27, 0
	s_add_u32 s13, s30, 0x100
	v_mov_b32_e32 v0, 0
	s_addc_u32 s15, s31, 0
	s_mov_b32 s30, 0
	v_mov_b32_e32 v1, v0
	v_mov_b32_e32 v2, v0
	v_mov_b32_e32 v3, v0
	v_mov_b32_e32 v4, v0
	v_mov_b32_e32 v5, v0
	v_mov_b32_e32 v6, v0
	v_mov_b32_e32 v7, v0
	v_mov_b32_e32 v8, v0
	v_mov_b32_e32 v9, v0
	v_mov_b32_e32 v10, v0
	v_mov_b32_e32 v11, v0
	v_mov_b32_e32 v12, v0
	v_mov_b32_e32 v13, v0
	v_mov_b32_e32 v14, v0
	v_mov_b32_e32 v15, v0
	v_mov_b32_e32 v16, v0
	v_mov_b32_e32 v17, v0
	v_mov_b32_e32 v18, v0
	v_mov_b32_e32 v19, v0
	v_mov_b32_e32 v20, v0
	v_mov_b32_e32 v21, v0
	v_mov_b32_e32 v22, v0
	v_mov_b32_e32 v23, v0
	v_mov_b32_e32 v24, v0
	v_mov_b32_e32 v25, v0
	v_mov_b32_e32 v26, v0
	v_mov_b32_e32 v27, v0
	v_mov_b32_e32 v28, v0
	v_mov_b32_e32 v29, v0
	v_mov_b32_e32 v30, v0
	v_mov_b32_e32 v31, v0
	v_mov_b32_e32 v52, v0
	v_mov_b32_e32 v53, v0
	v_mov_b32_e32 v54, v0
	v_mov_b32_e32 v55, v0
	v_mov_b32_e32 v60, v0
	v_mov_b32_e32 v61, v0
	v_mov_b32_e32 v62, v0
	v_mov_b32_e32 v63, v0
	v_mov_b32_e32 v68, v0
	v_mov_b32_e32 v69, v0
	v_mov_b32_e32 v70, v0
	v_mov_b32_e32 v71, v0
	v_mov_b32_e32 v76, v0
	v_mov_b32_e32 v77, v0
	v_mov_b32_e32 v78, v0
	v_mov_b32_e32 v79, v0
	v_mov_b32_e32 v80, v0
	v_mov_b32_e32 v81, v0
	v_mov_b32_e32 v82, v0
	v_mov_b32_e32 v83, v0
	v_mov_b32_e32 v84, v0
	v_mov_b32_e32 v85, v0
	v_mov_b32_e32 v86, v0
	v_mov_b32_e32 v87, v0
	v_mov_b32_e32 v88, v0
	v_mov_b32_e32 v89, v0
	v_mov_b32_e32 v90, v0
	v_mov_b32_e32 v91, v0
	v_mov_b32_e32 v92, v0
	v_mov_b32_e32 v93, v0
	v_mov_b32_e32 v94, v0
	v_mov_b32_e32 v95, v0
	v_mov_b32_e32 v32, v0
	v_mov_b32_e32 v33, v0
	v_mov_b32_e32 v34, v0
	v_mov_b32_e32 v35, v0
	v_mov_b32_e32 v36, v0
	v_mov_b32_e32 v37, v0
	v_mov_b32_e32 v38, v0
	v_mov_b32_e32 v39, v0
	v_mov_b32_e32 v40, v0
	v_mov_b32_e32 v41, v0
	v_mov_b32_e32 v42, v0
	v_mov_b32_e32 v43, v0
	v_mov_b32_e32 v44, v0
	v_mov_b32_e32 v45, v0
	v_mov_b32_e32 v46, v0
	v_mov_b32_e32 v47, v0
	v_mov_b32_e32 v48, v0
	v_mov_b32_e32 v49, v0
	v_mov_b32_e32 v50, v0
	v_mov_b32_e32 v51, v0
	v_mov_b32_e32 v56, v0
	v_mov_b32_e32 v57, v0
	v_mov_b32_e32 v58, v0
	v_mov_b32_e32 v59, v0
	v_mov_b32_e32 v64, v0
	v_mov_b32_e32 v65, v0
	v_mov_b32_e32 v66, v0
	v_mov_b32_e32 v67, v0
	v_mov_b32_e32 v72, v0
	v_mov_b32_e32 v73, v0
	v_mov_b32_e32 v74, v0
	v_mov_b32_e32 v75, v0
	v_mov_b32_e32 v96, v0
	v_mov_b32_e32 v97, v0
	v_mov_b32_e32 v98, v0
	v_mov_b32_e32 v99, v0
	v_mov_b32_e32 v100, v0
	v_mov_b32_e32 v101, v0
	v_mov_b32_e32 v102, v0
	v_mov_b32_e32 v103, v0
	v_mov_b32_e32 v104, v0
	v_mov_b32_e32 v105, v0
	v_mov_b32_e32 v106, v0
	v_mov_b32_e32 v107, v0
	v_mov_b32_e32 v108, v0
	v_mov_b32_e32 v109, v0
	v_mov_b32_e32 v110, v0
	v_mov_b32_e32 v111, v0
	v_mov_b32_e32 v112, v0
	v_mov_b32_e32 v113, v0
	v_mov_b32_e32 v114, v0
	v_mov_b32_e32 v115, v0
	v_mov_b32_e32 v116, v0
	v_mov_b32_e32 v117, v0
	v_mov_b32_e32 v118, v0
	v_mov_b32_e32 v119, v0
	v_mov_b32_e32 v120, v0
	v_mov_b32_e32 v121, v0
	v_mov_b32_e32 v122, v0
	v_mov_b32_e32 v123, v0
	v_mov_b32_e32 v124, v0
	v_mov_b32_e32 v125, v0
	v_mov_b32_e32 v126, v0
	v_mov_b32_e32 v127, v0
	.p2align	6

.LBB0_655:
	v_mov_b64_e32 v[0:1], s[2:3]
	s_ashr_i32 s9, s8, 31
	v_cmp_lt_i64_e32 vcc, s[10:11], v[0:1]
	s_lshl_b64 s[10:11], s[8:9], 20
	v_readlane_b32 s12, v255, 26
	v_readlane_b32 s13, v255, 27
	s_add_u32 s10, s12, s10
	s_addc_u32 s11, s13, s11
	s_and_b64 s[12:13], vcc, exec
	s_cselect_b32 s9, s11, s21
	s_cselect_b32 s15, s10, s20
	s_ashr_i32 s5, s4, 31
	s_lshl_b64 s[12:13], s[4:5], 20
	s_add_u32 s12, s26, s12
	s_addc_u32 s13, s27, s13
	s_and_b64 s[24:25], vcc, exec
	s_cselect_b32 s5, s13, s19
	s_cselect_b32 s17, s12, s18
	s_add_u32 s44, s18, 0x100
	s_addc_u32 s53, s19, 0
	s_add_u32 s18, s20, 0x80080
	v_mov_b32_e32 v0, 0
	s_addc_u32 s19, s21, 0
	s_mov_b32 s54, -2
	v_mov_b32_e32 v1, v0
	v_mov_b32_e32 v2, v0
	v_mov_b32_e32 v3, v0
	v_mov_b32_e32 v4, v0
	v_mov_b32_e32 v5, v0
	v_mov_b32_e32 v6, v0
	v_mov_b32_e32 v7, v0
	v_mov_b32_e32 v16, v0
	v_mov_b32_e32 v17, v0
	v_mov_b32_e32 v18, v0
	v_mov_b32_e32 v19, v0
	v_mov_b32_e32 v20, v0
	v_mov_b32_e32 v21, v0
	v_mov_b32_e32 v22, v0
	v_mov_b32_e32 v23, v0
	v_mov_b32_e32 v32, v0
	v_mov_b32_e32 v33, v0
	v_mov_b32_e32 v34, v0
	v_mov_b32_e32 v35, v0
	v_mov_b32_e32 v36, v0
	v_mov_b32_e32 v37, v0
	v_mov_b32_e32 v38, v0
	v_mov_b32_e32 v39, v0
	v_mov_b32_e32 v48, v0
	v_mov_b32_e32 v49, v0
	v_mov_b32_e32 v50, v0
	v_mov_b32_e32 v51, v0
	v_mov_b32_e32 v52, v0
	v_mov_b32_e32 v53, v0
	v_mov_b32_e32 v54, v0
	v_mov_b32_e32 v55, v0
	v_mov_b32_e32 v8, v0
	v_mov_b32_e32 v9, v0
	v_mov_b32_e32 v10, v0
	v_mov_b32_e32 v11, v0
	v_mov_b32_e32 v12, v0
	v_mov_b32_e32 v13, v0
	v_mov_b32_e32 v14, v0
	v_mov_b32_e32 v15, v0
	v_mov_b32_e32 v24, v0
	v_mov_b32_e32 v25, v0
	v_mov_b32_e32 v26, v0
	v_mov_b32_e32 v27, v0
	v_mov_b32_e32 v28, v0
	v_mov_b32_e32 v29, v0
	v_mov_b32_e32 v30, v0
	v_mov_b32_e32 v31, v0
	v_mov_b32_e32 v40, v0
	v_mov_b32_e32 v41, v0
	v_mov_b32_e32 v42, v0
	v_mov_b32_e32 v43, v0
	v_mov_b32_e32 v44, v0
	v_mov_b32_e32 v45, v0
	v_mov_b32_e32 v46, v0
	v_mov_b32_e32 v47, v0
	v_mov_b32_e32 v56, v0
	v_mov_b32_e32 v57, v0
	v_mov_b32_e32 v58, v0
	v_mov_b32_e32 v59, v0
	v_mov_b32_e32 v60, v0
	v_mov_b32_e32 v61, v0
	v_mov_b32_e32 v62, v0
	v_mov_b32_e32 v63, v0
	v_mov_b32_e32 v64, v0
	v_mov_b32_e32 v65, v0
	v_mov_b32_e32 v66, v0
	v_mov_b32_e32 v67, v0
	v_mov_b32_e32 v68, v0
	v_mov_b32_e32 v69, v0
	v_mov_b32_e32 v70, v0
	v_mov_b32_e32 v71, v0
	v_mov_b32_e32 v80, v0
	v_mov_b32_e32 v81, v0
	v_mov_b32_e32 v82, v0
	v_mov_b32_e32 v83, v0
	v_mov_b32_e32 v84, v0
	v_mov_b32_e32 v85, v0
	v_mov_b32_e32 v86, v0
	v_mov_b32_e32 v87, v0
	v_mov_b32_e32 v96, v0
	v_mov_b32_e32 v97, v0
	v_mov_b32_e32 v98, v0
	v_mov_b32_e32 v99, v0
	v_mov_b32_e32 v100, v0
	v_mov_b32_e32 v101, v0
	v_mov_b32_e32 v102, v0
	v_mov_b32_e32 v103, v0
	v_mov_b32_e32 v112, v0
	v_mov_b32_e32 v113, v0
	v_mov_b32_e32 v114, v0
	v_mov_b32_e32 v115, v0
	v_mov_b32_e32 v116, v0
	v_mov_b32_e32 v117, v0
	v_mov_b32_e32 v118, v0
	v_mov_b32_e32 v119, v0
	v_mov_b32_e32 v72, v0
	v_mov_b32_e32 v73, v0
	v_mov_b32_e32 v74, v0
	v_mov_b32_e32 v75, v0
	v_mov_b32_e32 v76, v0
	v_mov_b32_e32 v77, v0
	v_mov_b32_e32 v78, v0
	v_mov_b32_e32 v79, v0
	v_mov_b32_e32 v88, v0
	v_mov_b32_e32 v89, v0
	v_mov_b32_e32 v90, v0
	v_mov_b32_e32 v91, v0
	v_mov_b32_e32 v92, v0
	v_mov_b32_e32 v93, v0
	v_mov_b32_e32 v94, v0
	v_mov_b32_e32 v95, v0
	v_mov_b32_e32 v104, v0
	v_mov_b32_e32 v105, v0
	v_mov_b32_e32 v106, v0
	v_mov_b32_e32 v107, v0
	v_mov_b32_e32 v108, v0
	v_mov_b32_e32 v109, v0
	v_mov_b32_e32 v110, v0
	v_mov_b32_e32 v111, v0
	v_mov_b32_e32 v120, v0
	v_mov_b32_e32 v121, v0
	v_mov_b32_e32 v122, v0
	v_mov_b32_e32 v123, v0
	v_mov_b32_e32 v124, v0
	v_mov_b32_e32 v125, v0
	v_mov_b32_e32 v126, v0
	v_mov_b32_e32 v127, v0
	.p2align	6
